# v100: v99 with the 16 placeholder s_nop of the removed priority flips deleted from the GEMM main loop
# baseline (speedup 1.0000x reference)
.LBB0_394:
	s_add_i32 s13, s8, 2
	s_add_u32 s14, s2, 0x80
	s_addc_u32 s9, s3, 0
	s_add_i32 s38, 0, 0x10000
	s_cmp_eq_u32 s85, s8
	s_cselect_b32 s9, s19, s9
	s_cselect_b32 s8, s18, s14
	v_add_u32_e32 v0, s38, v237
	s_cselect_b32 s15, s21, s11
	s_cselect_b32 s14, s20, s10
	s_add_i32 s39, 0, 0x14000
	ds_read_b128 v[130:133], v0
	ds_read_b128 v[134:137], v0 offset:1024
	ds_read_b128 v[138:141], v0 offset:2048
	ds_read_b128 v[142:145], v0 offset:3072
	v_add_u32_e32 v0, s39, v237
	ds_read_b128 v[146:149], v0
	ds_read_b128 v[150:153], v0 offset:1024
	ds_read_b128 v[154:157], v0 offset:2048
	ds_read_b128 v[158:161], v0 offset:3072
	v_lshl_add_u64 v[214:215], s[2:3], 0, v[182:183]
	s_add_i32 m0, s57, 0xc000
	ds_read_b128 v[162:165], v238
	ds_read_b128 v[186:189], v238 offset:1024
	ds_read_b128 v[190:193], v238 offset:2048
	ds_read_b128 v[194:197], v238 offset:3072
	ds_read_b128 v[198:201], v238 offset:4096
	ds_read_b128 v[202:205], v238 offset:5120
	ds_read_b128 v[206:209], v238 offset:6144
	ds_read_b128 v[210:213], v238 offset:7168
	global_load_lds_dwordx4 v[214:215], off
	v_lshl_add_u64 v[214:215], s[2:3], 0, v[184:185]
	s_add_i32 m0, s57, 0xe000
	s_nop 0
	global_load_lds_dwordx4 v[214:215], off
	s_waitcnt vmcnt(8)
	s_waitcnt lgkmcnt(0)
	s_barrier
	s_waitcnt lgkmcnt(0)
	v_mfma_f32_16x16x32_bf16 v[126:129], v[130:133], v[162:165], v[126:129]
	v_mfma_f32_16x16x32_bf16 v[122:125], v[138:141], v[162:165], v[122:125]
	v_mfma_f32_16x16x32_bf16 v[110:113], v[130:133], v[190:193], v[110:113]
	v_mfma_f32_16x16x32_bf16 v[106:109], v[138:141], v[190:193], v[106:109]
	v_mfma_f32_16x16x32_bf16 v[94:97], v[130:133], v[198:201], v[94:97]
	v_mfma_f32_16x16x32_bf16 v[90:93], v[138:141], v[198:201], v[90:93]
	v_mfma_f32_16x16x32_bf16 v[78:81], v[130:133], v[206:209], v[78:81]
	v_mfma_f32_16x16x32_bf16 v[74:77], v[138:141], v[206:209], v[74:77]
	v_mfma_f32_16x16x32_bf16 v[126:129], v[134:137], v[186:189], v[126:129]
	v_mfma_f32_16x16x32_bf16 v[122:125], v[142:145], v[186:189], v[122:125]
	v_mfma_f32_16x16x32_bf16 v[110:113], v[134:137], v[194:197], v[110:113]
	v_mfma_f32_16x16x32_bf16 v[106:109], v[142:145], v[194:197], v[106:109]
	v_mfma_f32_16x16x32_bf16 v[94:97], v[134:137], v[202:205], v[94:97]
	v_mfma_f32_16x16x32_bf16 v[90:93], v[142:145], v[202:205], v[90:93]
	v_mfma_f32_16x16x32_bf16 v[78:81], v[134:137], v[210:213], v[78:81]
	v_mfma_f32_16x16x32_bf16 v[74:77], v[142:145], v[210:213], v[74:77]
	v_mfma_f32_16x16x32_bf16 v[118:121], v[146:149], v[162:165], v[118:121]
	v_mfma_f32_16x16x32_bf16 v[114:117], v[154:157], v[162:165], v[114:117]
	v_mfma_f32_16x16x32_bf16 v[102:105], v[146:149], v[190:193], v[102:105]
	v_mfma_f32_16x16x32_bf16 v[98:101], v[154:157], v[190:193], v[98:101]
	v_mfma_f32_16x16x32_bf16 v[86:89], v[146:149], v[198:201], v[86:89]
	v_mfma_f32_16x16x32_bf16 v[82:85], v[154:157], v[198:201], v[82:85]
	v_mfma_f32_16x16x32_bf16 v[70:73], v[146:149], v[206:209], v[70:73]
	v_mfma_f32_16x16x32_bf16 v[66:69], v[154:157], v[206:209], v[66:69]
	v_mfma_f32_16x16x32_bf16 v[118:121], v[150:153], v[186:189], v[118:121]
	v_mfma_f32_16x16x32_bf16 v[114:117], v[158:161], v[186:189], v[114:117]
	v_mfma_f32_16x16x32_bf16 v[102:105], v[150:153], v[194:197], v[102:105]
	v_mfma_f32_16x16x32_bf16 v[98:101], v[158:161], v[194:197], v[98:101]
	v_mfma_f32_16x16x32_bf16 v[86:89], v[150:153], v[202:205], v[86:89]
	v_mfma_f32_16x16x32_bf16 v[82:85], v[158:161], v[202:205], v[82:85]
	v_mfma_f32_16x16x32_bf16 v[70:73], v[150:153], v[210:213], v[70:73]
	v_mfma_f32_16x16x32_bf16 v[66:69], v[158:161], v[210:213], v[66:69]
	s_barrier
	s_add_i32 s38, s38, s56
	v_lshl_add_u64 v[214:215], s[14:15], 0, v[176:177]
	s_mov_b32 m0, s38
	ds_read_b128 v[162:165], v238 offset:16384
	ds_read_b128 v[186:189], v238 offset:17408
	ds_read_b128 v[190:193], v238 offset:18432
	ds_read_b128 v[194:197], v238 offset:19456
	ds_read_b128 v[198:201], v238 offset:20480
	ds_read_b128 v[202:205], v238 offset:21504
	ds_read_b128 v[206:209], v238 offset:22528
	ds_read_b128 v[210:213], v238 offset:23552
	global_load_lds_dwordx4 v[214:215], off
	s_add_i32 m0, s38, 0x2000
	v_lshl_add_u64 v[216:217], s[14:15], 0, v[172:173]
	s_add_u32 s14, s14, s70
	s_addc_u32 s15, s15, s71
	s_add_i32 s38, s39, s56
	global_load_lds_dwordx4 v[216:217], off
	v_lshl_add_u64 v[218:219], s[14:15], 0, v[176:177]
	s_mov_b32 m0, s38
	v_lshl_add_u64 v[220:221], s[14:15], 0, v[172:173]
	global_load_lds_dwordx4 v[218:219], off
	s_add_i32 m0, s38, 0x2000
	v_lshl_add_u64 v[222:223], s[8:9], 0, v[174:175]
	global_load_lds_dwordx4 v[220:221], off
	s_mov_b32 m0, s57
	v_lshl_add_u64 v[240:241], s[8:9], 0, v[170:171]
	global_load_lds_dwordx4 v[222:223], off
	s_mov_b32 m0, s58
	s_nop 0
	global_load_lds_dwordx4 v[240:241], off
	s_waitcnt vmcnt(8)
	s_waitcnt lgkmcnt(0)
	s_barrier
	s_waitcnt lgkmcnt(0)
	v_mfma_f32_16x16x32_bf16 v[62:65], v[130:133], v[162:165], v[62:65]
	v_mfma_f32_16x16x32_bf16 v[58:61], v[138:141], v[162:165], v[58:61]
	v_mfma_f32_16x16x32_bf16 v[46:49], v[130:133], v[190:193], v[46:49]
	v_mfma_f32_16x16x32_bf16 v[42:45], v[138:141], v[190:193], v[42:45]
	v_mfma_f32_16x16x32_bf16 v[30:33], v[130:133], v[198:201], v[30:33]
	v_mfma_f32_16x16x32_bf16 v[26:29], v[138:141], v[198:201], v[26:29]
	v_mfma_f32_16x16x32_bf16 v[14:17], v[130:133], v[206:209], v[14:17]
	v_mfma_f32_16x16x32_bf16 v[10:13], v[138:141], v[206:209], v[10:13]
	v_mfma_f32_16x16x32_bf16 v[62:65], v[134:137], v[186:189], v[62:65]
	v_mfma_f32_16x16x32_bf16 v[58:61], v[142:145], v[186:189], v[58:61]
	v_mfma_f32_16x16x32_bf16 v[46:49], v[134:137], v[194:197], v[46:49]
	v_mfma_f32_16x16x32_bf16 v[42:45], v[142:145], v[194:197], v[42:45]
	v_mfma_f32_16x16x32_bf16 v[30:33], v[134:137], v[202:205], v[30:33]
	v_mfma_f32_16x16x32_bf16 v[26:29], v[142:145], v[202:205], v[26:29]
	v_mfma_f32_16x16x32_bf16 v[14:17], v[134:137], v[210:213], v[14:17]
	v_mfma_f32_16x16x32_bf16 v[10:13], v[142:145], v[210:213], v[10:13]
	v_mfma_f32_16x16x32_bf16 v[54:57], v[146:149], v[162:165], v[54:57]
	v_mfma_f32_16x16x32_bf16 v[50:53], v[154:157], v[162:165], v[50:53]
	v_mfma_f32_16x16x32_bf16 v[38:41], v[146:149], v[190:193], v[38:41]
	v_mfma_f32_16x16x32_bf16 v[34:37], v[154:157], v[190:193], v[34:37]
	v_mfma_f32_16x16x32_bf16 v[22:25], v[146:149], v[198:201], v[22:25]
	v_mfma_f32_16x16x32_bf16 v[18:21], v[154:157], v[198:201], v[18:21]
	v_mfma_f32_16x16x32_bf16 v[6:9], v[146:149], v[206:209], v[6:9]
	v_mfma_f32_16x16x32_bf16 v[2:5], v[154:157], v[206:209], v[2:5]
	v_mfma_f32_16x16x32_bf16 v[54:57], v[150:153], v[186:189], v[54:57]
	v_mfma_f32_16x16x32_bf16 v[50:53], v[158:161], v[186:189], v[50:53]
	v_mfma_f32_16x16x32_bf16 v[38:41], v[150:153], v[194:197], v[38:41]
	v_mfma_f32_16x16x32_bf16 v[34:37], v[158:161], v[194:197], v[34:37]
	v_mfma_f32_16x16x32_bf16 v[22:25], v[150:153], v[202:205], v[22:25]
	v_mfma_f32_16x16x32_bf16 v[18:21], v[158:161], v[202:205], v[18:21]
	v_mfma_f32_16x16x32_bf16 v[6:9], v[150:153], v[210:213], v[6:9]
	v_mfma_f32_16x16x32_bf16 v[2:5], v[158:161], v[210:213], v[2:5]
	s_barrier
	s_add_i32 s14, 0, 0x18000
	v_add_u32_e32 v0, s14, v237
	s_add_i32 s15, 0, 0x1c000
	ds_read_b128 v[130:133], v0
	ds_read_b128 v[134:137], v0 offset:1024
	ds_read_b128 v[138:141], v0 offset:2048
	ds_read_b128 v[142:145], v0 offset:3072
	v_add_u32_e32 v0, s15, v237
	ds_read_b128 v[146:149], v0
	ds_read_b128 v[150:153], v0 offset:1024
	ds_read_b128 v[154:157], v0 offset:2048
	ds_read_b128 v[158:161], v0 offset:3072
	s_add_u32 s8, s8, s50
	s_addc_u32 s9, s9, s51
	s_mov_b32 m0, s59
	v_lshl_add_u64 v[242:243], s[8:9], 0, v[174:175]
	ds_read_b128 v[162:165], v238 offset:32768
	ds_read_b128 v[186:189], v238 offset:33792
	ds_read_b128 v[190:193], v238 offset:34816
	ds_read_b128 v[194:197], v238 offset:35840
	ds_read_b128 v[198:201], v238 offset:36864
	ds_read_b128 v[202:205], v238 offset:37888
	ds_read_b128 v[206:209], v238 offset:38912
	ds_read_b128 v[210:213], v238 offset:39936
	global_load_lds_dwordx4 v[242:243], off
	v_lshl_add_u64 v[242:243], s[8:9], 0, v[170:171]
	s_mov_b32 m0, s60
	s_nop 0
	global_load_lds_dwordx4 v[242:243], off
	s_waitcnt vmcnt(8)
	s_waitcnt lgkmcnt(0)
	s_barrier
	s_waitcnt lgkmcnt(0)
	v_mfma_f32_16x16x32_bf16 v[126:129], v[130:133], v[162:165], v[126:129]
	v_mfma_f32_16x16x32_bf16 v[122:125], v[138:141], v[162:165], v[122:125]
	v_mfma_f32_16x16x32_bf16 v[110:113], v[130:133], v[190:193], v[110:113]
	v_mfma_f32_16x16x32_bf16 v[106:109], v[138:141], v[190:193], v[106:109]
	v_mfma_f32_16x16x32_bf16 v[94:97], v[130:133], v[198:201], v[94:97]
	v_mfma_f32_16x16x32_bf16 v[90:93], v[138:141], v[198:201], v[90:93]
	v_mfma_f32_16x16x32_bf16 v[78:81], v[130:133], v[206:209], v[78:81]
	v_mfma_f32_16x16x32_bf16 v[74:77], v[138:141], v[206:209], v[74:77]
	v_mfma_f32_16x16x32_bf16 v[126:129], v[134:137], v[186:189], v[126:129]
	v_mfma_f32_16x16x32_bf16 v[122:125], v[142:145], v[186:189], v[122:125]
	v_mfma_f32_16x16x32_bf16 v[110:113], v[134:137], v[194:197], v[110:113]
	v_mfma_f32_16x16x32_bf16 v[106:109], v[142:145], v[194:197], v[106:109]
	v_mfma_f32_16x16x32_bf16 v[94:97], v[134:137], v[202:205], v[94:97]
	v_mfma_f32_16x16x32_bf16 v[90:93], v[142:145], v[202:205], v[90:93]
	v_mfma_f32_16x16x32_bf16 v[78:81], v[134:137], v[210:213], v[78:81]
	v_mfma_f32_16x16x32_bf16 v[74:77], v[142:145], v[210:213], v[74:77]
	v_mfma_f32_16x16x32_bf16 v[118:121], v[146:149], v[162:165], v[118:121]
	v_mfma_f32_16x16x32_bf16 v[114:117], v[154:157], v[162:165], v[114:117]
	v_mfma_f32_16x16x32_bf16 v[102:105], v[146:149], v[190:193], v[102:105]
	v_mfma_f32_16x16x32_bf16 v[98:101], v[154:157], v[190:193], v[98:101]
	v_mfma_f32_16x16x32_bf16 v[86:89], v[146:149], v[198:201], v[86:89]
	v_mfma_f32_16x16x32_bf16 v[82:85], v[154:157], v[198:201], v[82:85]
	v_mfma_f32_16x16x32_bf16 v[70:73], v[146:149], v[206:209], v[70:73]
	v_mfma_f32_16x16x32_bf16 v[66:69], v[154:157], v[206:209], v[66:69]
	v_mfma_f32_16x16x32_bf16 v[118:121], v[150:153], v[186:189], v[118:121]
	v_mfma_f32_16x16x32_bf16 v[114:117], v[158:161], v[186:189], v[114:117]
	v_mfma_f32_16x16x32_bf16 v[102:105], v[150:153], v[194:197], v[102:105]
	v_mfma_f32_16x16x32_bf16 v[98:101], v[158:161], v[194:197], v[98:101]
	v_mfma_f32_16x16x32_bf16 v[86:89], v[150:153], v[202:205], v[86:89]
	v_mfma_f32_16x16x32_bf16 v[82:85], v[158:161], v[202:205], v[82:85]
	v_mfma_f32_16x16x32_bf16 v[70:73], v[150:153], v[210:213], v[70:73]
	v_mfma_f32_16x16x32_bf16 v[66:69], v[158:161], v[210:213], v[66:69]
	s_barrier
	s_add_i32 s8, s14, s56
	v_lshl_add_u64 v[214:215], v[214:215], 0, s[4:5]
	s_mov_b32 m0, s8
	ds_read_b128 v[162:165], v238 offset:49152
	ds_read_b128 v[186:189], v238 offset:50176
	ds_read_b128 v[190:193], v238 offset:51200
	ds_read_b128 v[194:197], v238 offset:52224
	ds_read_b128 v[198:201], v238 offset:53248
	ds_read_b128 v[202:205], v238 offset:54272
	ds_read_b128 v[206:209], v238 offset:55296
	ds_read_b128 v[210:213], v238 offset:56320
	global_load_lds_dwordx4 v[214:215], off
	v_lshl_add_u64 v[214:215], v[216:217], 0, s[4:5]
	s_add_i32 m0, s8, 0x2000
	s_add_i32 s8, s15, s56
	global_load_lds_dwordx4 v[214:215], off
	v_lshl_add_u64 v[214:215], v[218:219], 0, s[4:5]
	s_mov_b32 m0, s8
	s_nop 0
	global_load_lds_dwordx4 v[214:215], off
	v_lshl_add_u64 v[214:215], v[220:221], 0, s[4:5]
	s_add_i32 m0, s8, 0x2000
	s_nop 0
	global_load_lds_dwordx4 v[214:215], off
	v_lshl_add_u64 v[214:215], v[222:223], 0, s[4:5]
	s_mov_b32 m0, s69
	s_nop 0
	global_load_lds_dwordx4 v[214:215], off
	v_lshl_add_u64 v[214:215], v[240:241], 0, s[4:5]
	s_mov_b32 m0, s84
	s_nop 0
	global_load_lds_dwordx4 v[214:215], off
	s_waitcnt vmcnt(8)
	s_waitcnt lgkmcnt(0)
	s_barrier
	s_waitcnt lgkmcnt(0)
	v_mfma_f32_16x16x32_bf16 v[62:65], v[130:133], v[162:165], v[62:65]
	v_mfma_f32_16x16x32_bf16 v[58:61], v[138:141], v[162:165], v[58:61]
	v_mfma_f32_16x16x32_bf16 v[46:49], v[130:133], v[190:193], v[46:49]
	v_mfma_f32_16x16x32_bf16 v[42:45], v[138:141], v[190:193], v[42:45]
	v_mfma_f32_16x16x32_bf16 v[30:33], v[130:133], v[198:201], v[30:33]
	v_mfma_f32_16x16x32_bf16 v[26:29], v[138:141], v[198:201], v[26:29]
	v_mfma_f32_16x16x32_bf16 v[14:17], v[130:133], v[206:209], v[14:17]
	v_mfma_f32_16x16x32_bf16 v[10:13], v[138:141], v[206:209], v[10:13]
	v_mfma_f32_16x16x32_bf16 v[62:65], v[134:137], v[186:189], v[62:65]
	v_mfma_f32_16x16x32_bf16 v[58:61], v[142:145], v[186:189], v[58:61]
	v_mfma_f32_16x16x32_bf16 v[46:49], v[134:137], v[194:197], v[46:49]
	v_mfma_f32_16x16x32_bf16 v[42:45], v[142:145], v[194:197], v[42:45]
	v_mfma_f32_16x16x32_bf16 v[30:33], v[134:137], v[202:205], v[30:33]
	v_mfma_f32_16x16x32_bf16 v[26:29], v[142:145], v[202:205], v[26:29]
	v_mfma_f32_16x16x32_bf16 v[14:17], v[134:137], v[210:213], v[14:17]
	v_mfma_f32_16x16x32_bf16 v[10:13], v[142:145], v[210:213], v[10:13]
	v_mfma_f32_16x16x32_bf16 v[54:57], v[146:149], v[162:165], v[54:57]
	v_mfma_f32_16x16x32_bf16 v[50:53], v[154:157], v[162:165], v[50:53]
	v_mfma_f32_16x16x32_bf16 v[38:41], v[146:149], v[190:193], v[38:41]
	v_mfma_f32_16x16x32_bf16 v[34:37], v[154:157], v[190:193], v[34:37]
	v_mfma_f32_16x16x32_bf16 v[22:25], v[146:149], v[198:201], v[22:25]
	v_mfma_f32_16x16x32_bf16 v[18:21], v[154:157], v[198:201], v[18:21]
	v_mfma_f32_16x16x32_bf16 v[6:9], v[146:149], v[206:209], v[6:9]
	v_mfma_f32_16x16x32_bf16 v[2:5], v[154:157], v[206:209], v[2:5]
	v_mfma_f32_16x16x32_bf16 v[54:57], v[150:153], v[186:189], v[54:57]
	v_mfma_f32_16x16x32_bf16 v[50:53], v[158:161], v[186:189], v[50:53]
	v_mfma_f32_16x16x32_bf16 v[38:41], v[150:153], v[194:197], v[38:41]
	v_mfma_f32_16x16x32_bf16 v[34:37], v[158:161], v[194:197], v[34:37]
	v_mfma_f32_16x16x32_bf16 v[22:25], v[150:153], v[202:205], v[22:25]
	v_mfma_f32_16x16x32_bf16 v[18:21], v[158:161], v[202:205], v[18:21]
	v_mfma_f32_16x16x32_bf16 v[6:9], v[150:153], v[210:213], v[6:9]
	v_mfma_f32_16x16x32_bf16 v[2:5], v[158:161], v[210:213], v[2:5]
	s_barrier
	s_add_u32 s2, s2, 0x100
	s_addc_u32 s3, s3, 0
	s_add_u32 s10, s10, 0x100
	s_addc_u32 s11, s11, 0
	s_cmp_ge_u32 s13, s66
	s_mov_b32 s8, s13
	s_cbranch_scc0 .LBB0_394
	s_and_b64 vcc, exec, s[94:95]
	s_cbranch_vccz .LBB0_397
	s_barrier
